# grid barrier: XCD leaders poll the TOP arrival counter directly instead of waiting for the last leader's TOPGEN bump (one fewer atomic round trip per barrier)
# speedup vs baseline: 1.0033x; 1.0026x over previous
.LBB0_194:
	s_andn2_saveexec_b64 s[4:5], s[4:5]
	s_cbranch_execz .LBB0_210
	v_mov_b32_e32 v1, s36
	v_add_co_u32_e32 v2, vcc, 0x3000, v1
	v_mov_b32_e32 v1, s37
	buffer_wbl2 sc1
	s_waitcnt vmcnt(0)
	v_addc_co_u32_e32 v3, vcc, 0, v1, vcc
	v_mov_b32_e32 v1, 1
	flat_atomic_add v1, v[2:3], v1 offset:1024 sc0
	v_cvt_f32_u32_e32 v2, v0
	v_sub_u32_e32 v3, 0, v0
	s_add_u32 s4, s36, 0x3400
	s_addc_u32 s5, s37, 0
	v_rcp_iflag_f32_e32 v2, v2
	s_mov_b64 s[8:9], -1
	v_mul_f32_e32 v2, 0x4f7ffffe, v2
	v_cvt_u32_f32_e32 v2, v2
	v_mul_lo_u32 v3, v3, v2
	v_mul_hi_u32 v3, v2, v3
	v_add_u32_e32 v2, v2, v3
	s_waitcnt vmcnt(0) lgkmcnt(0)
	v_mul_hi_u32 v2, v1, v2
	v_mul_lo_u32 v4, v2, v0
	v_add_u32_e32 v3, 1, v1
	v_sub_u32_e32 v1, v1, v4
	v_add_u32_e32 v5, 1, v2
	v_cmp_ge_u32_e32 vcc, v1, v0
	v_sub_u32_e32 v4, v1, v0
	s_nop 0
	v_cndmask_b32_e32 v2, v2, v5, vcc
	v_cndmask_b32_e32 v1, v1, v4, vcc
	v_add_u32_e32 v4, 1, v2
	v_cmp_ge_u32_e32 vcc, v1, v0
	s_nop 1
	v_cndmask_b32_e32 v2, v2, v4, vcc
	v_mad_u64_u32 v[0:1], s[6:7], v0, v2, v[0:1]
	v_cmp_ne_u32_e32 vcc, v3, v0
	v_mov_b32_e32 v3, v0
	v_mov_b64_e32 v[0:1], s[4:5]
	s_and_saveexec_b64 s[6:7], vcc
	s_cbranch_execz .LBB0_207
	v_mov_b64_e32 v[0:1], s[4:5]
	flat_load_dword v0, v[0:1] sc1
	s_mov_b64 s[12:13], 0
	s_waitcnt vmcnt(0) lgkmcnt(0)
	v_cmp_lt_u32_e32 vcc, v0, v3
	s_and_saveexec_b64 s[10:11], vcc
	s_cbranch_execz .LBB0_206
	s_add_u32 s8, s36, 0x200
	s_addc_u32 s9, s37, 0
	s_mov_b32 s25, 1
	s_branch .LBB0_199

.LBB0_204:
	v_mov_b64_e32 v[0:1], s[4:5]
	flat_load_dword v0, v[0:1] sc1
	s_add_i32 s25, s25, 1
	s_or_b64 s[16:17], s[16:17], exec
	s_waitcnt vmcnt(0) lgkmcnt(0)
	v_cmp_ge_u32_e32 vcc, v0, v3
	s_orn2_b64 s[20:21], vcc, exec
	s_branch .LBB0_198

.LBB0_207:
	s_or_b64 exec, exec, s[6:7]
	s_and_saveexec_b64 s[4:5], s[8:9]
	s_cbranch_execz .LBB0_209
	v_mov_b32_e32 v2, 1
	flat_atomic_add v[0:1], v2 offset:256

.LBB0_388:
	s_andn2_saveexec_b64 s[8:9], s[8:9]
	s_cbranch_execz .LBB0_404
	v_mov_b32_e32 v1, s42
	v_add_co_u32_e32 v2, vcc, 0x3000, v1
	v_mov_b32_e32 v1, s43
	buffer_wbl2 sc1
	s_waitcnt vmcnt(0)
	v_addc_co_u32_e32 v3, vcc, 0, v1, vcc
	flat_atomic_add v1, v[2:3], v228 offset:1024 sc0
	v_cvt_f32_u32_e32 v2, v0
	v_sub_u32_e32 v3, 0, v0
	s_mov_b64 s[12:13], -1
	v_rcp_iflag_f32_e32 v2, v2
	s_nop 0
	v_mul_f32_e32 v2, 0x4f7ffffe, v2
	v_cvt_u32_f32_e32 v2, v2
	v_mul_lo_u32 v3, v3, v2
	v_mul_hi_u32 v3, v2, v3
	v_add_u32_e32 v2, v2, v3
	s_waitcnt vmcnt(0) lgkmcnt(0)
	v_mul_hi_u32 v2, v1, v2
	v_mul_lo_u32 v3, v2, v0
	v_sub_u32_e32 v3, v1, v3
	v_cmp_ge_u32_e32 vcc, v3, v0
	v_add_u32_e32 v4, 1, v2
	s_nop 0
	v_cndmask_b32_e32 v2, v2, v4, vcc
	v_sub_u32_e32 v4, v3, v0
	v_cndmask_b32_e32 v3, v3, v4, vcc
	v_cmp_ge_u32_e32 vcc, v3, v0
	v_add_u32_e32 v3, 1, v2
	s_nop 0
	v_cndmask_b32_e32 v2, v2, v3, vcc
	v_add_u32_e32 v3, 1, v1
	v_mad_u64_u32 v[0:1], s[8:9], v0, v2, v[0:1]
	s_add_u32 s8, s42, 0x3400
	s_addc_u32 s9, s43, 0
	v_cmp_ne_u32_e32 vcc, v3, v0
	v_mov_b32_e32 v3, v0
	v_mov_b64_e32 v[0:1], s[8:9]
	s_and_saveexec_b64 s[10:11], vcc
	s_cbranch_execz .LBB0_401
	v_mov_b64_e32 v[0:1], s[8:9]
	flat_load_dword v0, v[0:1] sc1
	s_mov_b64 s[16:17], 0
	s_waitcnt vmcnt(0) lgkmcnt(0)
	v_cmp_lt_u32_e32 vcc, v0, v3
	s_and_saveexec_b64 s[14:15], vcc
	s_cbranch_execz .LBB0_400
	s_add_u32 s12, s42, 0x200
	s_addc_u32 s13, s43, 0
	s_mov_b32 s7, 1
	s_branch .LBB0_393

.LBB0_398:
	v_mov_b64_e32 v[0:1], s[8:9]
	flat_load_dword v0, v[0:1] sc1
	s_add_i32 s7, s7, 1
	s_or_b64 s[22:23], s[22:23], exec
	s_waitcnt vmcnt(0) lgkmcnt(0)
	v_cmp_ge_u32_e32 vcc, v0, v3
	s_orn2_b64 s[20:21], vcc, exec
	s_branch .LBB0_392

.LBB0_401:
	s_or_b64 exec, exec, s[10:11]
	s_and_saveexec_b64 s[8:9], s[12:13]
	s_cbranch_execz .LBB0_403
	flat_atomic_add v[0:1], v228 offset:256

.LBB0_770:
	s_andn2_saveexec_b64 s[12:13], s[12:13]
	s_cbranch_execz .LBB0_786
	v_mov_b32_e32 v1, s54
	v_add_co_u32_e32 v2, vcc, 0x3000, v1
	v_mov_b32_e32 v1, s55
	buffer_wbl2 sc1
	s_waitcnt vmcnt(0)
	v_addc_co_u32_e32 v3, vcc, 0, v1, vcc
	flat_atomic_add v1, v[2:3], v228 offset:1024 sc0
	v_cvt_f32_u32_e32 v2, v0
	v_sub_u32_e32 v3, 0, v0
	s_add_u32 s14, s54, 0x3400
	s_addc_u32 s15, s55, 0
	v_rcp_iflag_f32_e32 v2, v2
	s_mov_b64 s[18:19], -1
	v_mul_f32_e32 v2, 0x4f7ffffe, v2
	v_cvt_u32_f32_e32 v2, v2
	v_mul_lo_u32 v3, v3, v2
	v_mul_hi_u32 v3, v2, v3
	v_add_u32_e32 v2, v2, v3
	s_waitcnt vmcnt(0) lgkmcnt(0)
	v_mul_hi_u32 v2, v1, v2
	v_mul_lo_u32 v3, v2, v0
	v_sub_u32_e32 v3, v1, v3
	v_cmp_ge_u32_e32 vcc, v3, v0
	v_add_u32_e32 v4, 1, v2
	s_nop 0
	v_cndmask_b32_e32 v2, v2, v4, vcc
	v_sub_u32_e32 v4, v3, v0
	v_cndmask_b32_e32 v3, v3, v4, vcc
	v_cmp_ge_u32_e32 vcc, v3, v0
	v_add_u32_e32 v3, 1, v2
	s_nop 0
	v_cndmask_b32_e32 v2, v2, v3, vcc
	v_add_u32_e32 v3, 1, v1
	v_mad_u64_u32 v[0:1], s[8:9], v0, v2, v[0:1]
	v_cmp_ne_u32_e32 vcc, v3, v0
	v_mov_b32_e32 v3, v0
	v_mov_b64_e32 v[0:1], s[14:15]
	s_and_saveexec_b64 s[16:17], vcc
	s_cbranch_execz .LBB0_783
	v_mov_b64_e32 v[0:1], s[14:15]
	flat_load_dword v0, v[0:1] sc1
	s_mov_b64 s[22:23], 0
	s_waitcnt vmcnt(0) lgkmcnt(0)
	v_cmp_lt_u32_e32 vcc, v0, v3
	s_and_saveexec_b64 s[20:21], vcc
	s_cbranch_execz .LBB0_782
	s_add_u32 s18, s54, 0x200
	s_addc_u32 s19, s55, 0
	s_mov_b32 s7, 1
	s_branch .LBB0_775

.LBB0_780:
	v_mov_b64_e32 v[0:1], s[14:15]
	flat_load_dword v0, v[0:1] sc1
	s_add_i32 s7, s7, 1
	s_or_b64 s[28:29], s[28:29], exec
	s_waitcnt vmcnt(0) lgkmcnt(0)
	v_cmp_ge_u32_e32 vcc, v0, v3
	s_orn2_b64 s[26:27], vcc, exec
	s_branch .LBB0_774

.LBB0_783:
	s_or_b64 exec, exec, s[16:17]
	s_and_saveexec_b64 s[14:15], s[18:19]
	s_cbranch_execz .LBB0_785
	flat_atomic_add v[0:1], v228 offset:256

.LBB0_890:
	s_andn2_saveexec_b64 s[8:9], s[12:13]
	s_cbranch_execz .LBB0_906
	v_mov_b32_e32 v1, s54
	v_add_co_u32_e32 v2, vcc, 0x3000, v1
	v_mov_b32_e32 v1, s55
	buffer_wbl2 sc1
	s_waitcnt vmcnt(0)
	v_addc_co_u32_e32 v3, vcc, 0, v1, vcc
	flat_atomic_add v1, v[2:3], v228 offset:1024 sc0
	v_cvt_f32_u32_e32 v2, v0
	v_sub_u32_e32 v3, 0, v0
	s_add_u32 s12, s54, 0x3400
	s_addc_u32 s13, s55, 0
	v_rcp_iflag_f32_e32 v2, v2
	s_mov_b64 s[16:17], -1
	v_mul_f32_e32 v2, 0x4f7ffffe, v2
	v_cvt_u32_f32_e32 v2, v2
	v_mul_lo_u32 v3, v3, v2
	v_mul_hi_u32 v3, v2, v3
	v_add_u32_e32 v2, v2, v3
	s_waitcnt vmcnt(0) lgkmcnt(0)
	v_mul_hi_u32 v2, v1, v2
	v_mul_lo_u32 v3, v2, v0
	v_sub_u32_e32 v3, v1, v3
	v_cmp_ge_u32_e32 vcc, v3, v0
	v_add_u32_e32 v4, 1, v2
	s_nop 0
	v_cndmask_b32_e32 v2, v2, v4, vcc
	v_sub_u32_e32 v4, v3, v0
	v_cndmask_b32_e32 v3, v3, v4, vcc
	v_cmp_ge_u32_e32 vcc, v3, v0
	v_add_u32_e32 v3, 1, v2
	s_nop 0
	v_cndmask_b32_e32 v2, v2, v3, vcc
	v_add_u32_e32 v3, 1, v1
	v_mad_u64_u32 v[0:1], s[8:9], v0, v2, v[0:1]
	v_cmp_ne_u32_e32 vcc, v3, v0
	v_mov_b32_e32 v3, v0
	v_mov_b64_e32 v[0:1], s[12:13]
	s_and_saveexec_b64 s[14:15], vcc
	s_cbranch_execz .LBB0_903
	v_mov_b64_e32 v[0:1], s[12:13]
	flat_load_dword v0, v[0:1] sc1
	s_mov_b64 s[20:21], 0
	s_waitcnt vmcnt(0) lgkmcnt(0)
	v_cmp_lt_u32_e32 vcc, v0, v3
	s_and_saveexec_b64 s[18:19], vcc
	s_cbranch_execz .LBB0_902
	s_add_u32 s16, s54, 0x200
	s_addc_u32 s17, s55, 0
	s_mov_b32 s7, 1
	s_branch .LBB0_895

.LBB0_900:
	v_mov_b64_e32 v[0:1], s[12:13]
	flat_load_dword v0, v[0:1] sc1
	s_add_i32 s7, s7, 1
	s_or_b64 s[26:27], s[26:27], exec
	s_waitcnt vmcnt(0) lgkmcnt(0)
	v_cmp_ge_u32_e32 vcc, v0, v3
	s_orn2_b64 s[24:25], vcc, exec
	s_branch .LBB0_894

.LBB0_903:
	s_or_b64 exec, exec, s[14:15]
	s_and_saveexec_b64 s[12:13], s[16:17]
	s_cbranch_execz .LBB0_905
	flat_atomic_add v[0:1], v228 offset:256

.LBB0_1136:
	s_andn2_saveexec_b64 s[8:9], s[12:13]
	s_cbranch_execz .LBB0_1152
	v_mov_b32_e32 v1, s50
	v_add_co_u32_e32 v2, vcc, 0x3000, v1
	v_mov_b32_e32 v1, s51
	buffer_wbl2 sc1
	s_waitcnt vmcnt(0)
	v_addc_co_u32_e32 v3, vcc, 0, v1, vcc
	flat_atomic_add v1, v[2:3], v228 offset:1024 sc0
	v_cvt_f32_u32_e32 v2, v0
	v_sub_u32_e32 v3, 0, v0
	s_add_u32 s12, s50, 0x3400
	s_addc_u32 s13, s51, 0
	v_rcp_iflag_f32_e32 v2, v2
	s_mov_b64 s[16:17], -1
	v_mul_f32_e32 v2, 0x4f7ffffe, v2
	v_cvt_u32_f32_e32 v2, v2
	v_mul_lo_u32 v3, v3, v2
	v_mul_hi_u32 v3, v2, v3
	v_add_u32_e32 v2, v2, v3
	s_waitcnt vmcnt(0) lgkmcnt(0)
	v_mul_hi_u32 v2, v1, v2
	v_mul_lo_u32 v3, v2, v0
	v_sub_u32_e32 v3, v1, v3
	v_cmp_ge_u32_e32 vcc, v3, v0
	v_add_u32_e32 v4, 1, v2
	s_nop 0
	v_cndmask_b32_e32 v2, v2, v4, vcc
	v_sub_u32_e32 v4, v3, v0
	v_cndmask_b32_e32 v3, v3, v4, vcc
	v_cmp_ge_u32_e32 vcc, v3, v0
	v_add_u32_e32 v3, 1, v2
	s_nop 0
	v_cndmask_b32_e32 v2, v2, v3, vcc
	v_add_u32_e32 v3, 1, v1
	v_mad_u64_u32 v[0:1], s[8:9], v0, v2, v[0:1]
	v_cmp_ne_u32_e32 vcc, v3, v0
	v_mov_b32_e32 v3, v0
	v_mov_b64_e32 v[0:1], s[12:13]
	s_and_saveexec_b64 s[14:15], vcc
	s_cbranch_execz .LBB0_1149
	v_mov_b64_e32 v[0:1], s[12:13]
	flat_load_dword v0, v[0:1] sc1
	s_mov_b64 s[20:21], 0
	s_waitcnt vmcnt(0) lgkmcnt(0)
	v_cmp_lt_u32_e32 vcc, v0, v3
	s_and_saveexec_b64 s[18:19], vcc
	s_cbranch_execz .LBB0_1148
	s_add_u32 s16, s50, 0x200
	s_addc_u32 s17, s51, 0
	s_mov_b32 s7, 1
	s_branch .LBB0_1141

.LBB0_1251:
	s_andn2_saveexec_b64 s[8:9], s[10:11]
	s_cbranch_execz .LBB0_1267
	v_mov_b32_e32 v1, s50
	v_add_co_u32_e32 v2, vcc, 0x3000, v1
	v_mov_b32_e32 v1, s51
	buffer_wbl2 sc1
	s_waitcnt vmcnt(0)
	v_addc_co_u32_e32 v3, vcc, 0, v1, vcc
	flat_atomic_add v1, v[2:3], v228 offset:1024 sc0
	v_cvt_f32_u32_e32 v2, v0
	v_sub_u32_e32 v3, 0, v0
	s_add_u32 s10, s50, 0x3400
	s_addc_u32 s11, s51, 0
	v_rcp_iflag_f32_e32 v2, v2
	s_mov_b64 s[14:15], -1
	v_mul_f32_e32 v2, 0x4f7ffffe, v2
	v_cvt_u32_f32_e32 v2, v2
	v_mul_lo_u32 v3, v3, v2
	v_mul_hi_u32 v3, v2, v3
	v_add_u32_e32 v2, v2, v3
	s_waitcnt vmcnt(0) lgkmcnt(0)
	v_mul_hi_u32 v2, v1, v2
	v_mul_lo_u32 v3, v2, v0
	v_sub_u32_e32 v3, v1, v3
	v_cmp_ge_u32_e32 vcc, v3, v0
	v_add_u32_e32 v4, 1, v2
	s_nop 0
	v_cndmask_b32_e32 v2, v2, v4, vcc
	v_sub_u32_e32 v4, v3, v0
	v_cndmask_b32_e32 v3, v3, v4, vcc
	v_cmp_ge_u32_e32 vcc, v3, v0
	v_add_u32_e32 v3, 1, v2
	s_nop 0
	v_cndmask_b32_e32 v2, v2, v3, vcc
	v_add_u32_e32 v3, 1, v1
	v_mad_u64_u32 v[0:1], s[8:9], v0, v2, v[0:1]
	v_cmp_ne_u32_e32 vcc, v3, v0
	v_mov_b32_e32 v3, v0
	v_mov_b64_e32 v[0:1], s[10:11]
	s_and_saveexec_b64 s[12:13], vcc
	s_cbranch_execz .LBB0_1264
	v_mov_b64_e32 v[0:1], s[10:11]
	flat_load_dword v0, v[0:1] sc1
	s_mov_b64 s[18:19], 0
	s_waitcnt vmcnt(0) lgkmcnt(0)
	v_cmp_lt_u32_e32 vcc, v0, v3
	s_and_saveexec_b64 s[16:17], vcc
	s_cbranch_execz .LBB0_1263
	s_add_u32 s14, s50, 0x200
	s_addc_u32 s15, s51, 0
	s_mov_b32 s7, 1
	s_branch .LBB0_1256

.LBB0_1261:
	v_mov_b64_e32 v[0:1], s[10:11]
	flat_load_dword v0, v[0:1] sc1
	s_add_i32 s7, s7, 1
	s_or_b64 s[24:25], s[24:25], exec
	s_waitcnt vmcnt(0) lgkmcnt(0)
	v_cmp_ge_u32_e32 vcc, v0, v3
	s_orn2_b64 s[22:23], vcc, exec
	s_branch .LBB0_1255

.LBB0_1264:
	s_or_b64 exec, exec, s[12:13]
	s_and_saveexec_b64 s[10:11], s[14:15]
	s_cbranch_execz .LBB0_1266
	flat_atomic_add v[0:1], v228 offset:256

.LBB0_1402:
	v_mov_b32_e32 v1, s42
	v_add_co_u32_e32 v2, vcc, 0x3000, v1
	v_mov_b32_e32 v1, s43
	buffer_wbl2 sc1
	s_waitcnt vmcnt(0)
	v_addc_co_u32_e32 v3, vcc, 0, v1, vcc
	flat_atomic_add v1, v[2:3], v228 offset:1024 sc0
	v_cvt_f32_u32_e32 v2, v0
	v_sub_u32_e32 v3, 0, v0
	s_mov_b64 s[12:13], -1
	v_rcp_iflag_f32_e32 v2, v2
	s_nop 0
	v_mul_f32_e32 v2, 0x4f7ffffe, v2
	v_cvt_u32_f32_e32 v2, v2
	v_mul_lo_u32 v3, v3, v2
	v_mul_hi_u32 v3, v2, v3
	v_add_u32_e32 v2, v2, v3
	s_waitcnt vmcnt(0) lgkmcnt(0)
	v_mul_hi_u32 v2, v1, v2
	v_mul_lo_u32 v3, v2, v0
	v_sub_u32_e32 v3, v1, v3
	v_cmp_ge_u32_e32 vcc, v3, v0
	v_add_u32_e32 v4, 1, v2
	s_nop 0
	v_cndmask_b32_e32 v2, v2, v4, vcc
	v_sub_u32_e32 v4, v3, v0
	v_cndmask_b32_e32 v3, v3, v4, vcc
	v_cmp_ge_u32_e32 vcc, v3, v0
	v_add_u32_e32 v3, 1, v2
	s_nop 0
	v_cndmask_b32_e32 v2, v2, v3, vcc
	v_add_u32_e32 v3, 1, v1
	v_mad_u64_u32 v[0:1], s[8:9], v0, v2, v[0:1]
	s_add_u32 s8, s42, 0x3400
	s_addc_u32 s9, s43, 0
	v_cmp_ne_u32_e32 vcc, v3, v0
	v_mov_b32_e32 v3, v0
	v_mov_b64_e32 v[0:1], s[8:9]
	s_and_saveexec_b64 s[10:11], vcc
	s_cbranch_execz .LBB0_1414
	v_mov_b64_e32 v[0:1], s[8:9]
	flat_load_dword v0, v[0:1] sc1
	s_mov_b64 s[16:17], 0
	s_waitcnt vmcnt(0) lgkmcnt(0)
	v_cmp_lt_u32_e32 vcc, v0, v3
	s_and_saveexec_b64 s[14:15], vcc
	s_cbranch_execz .LBB0_1413
	s_add_u32 s12, s42, 0x200
	s_addc_u32 s13, s43, 0
	s_mov_b32 s7, 1
	s_branch .LBB0_1406

.LBB0_1415:
	flat_atomic_add v[0:1], v228 offset:256
	s_getpc_b64 s[98:99]
